# half of the XCDs enter P5 ~14us late (skew kept by XCD-local barriers) to interleave the two halves' epilogue store bursts
# speedup vs baseline: 1.0020x; 1.0013x over previous
;     __device__ bool next(int i, Unit& u) const {
;         const long L = (long)i * G + c; if (L >= nwg) return false;
;         int wgid = (int)L; { const int q = nwg / NXCD, r = nwg % NXCD, xcd = wgid % NXCD, off = wgid / NXCD; wgid = (xcd < r ? xcd * (q + 1) : r * (q + 1) + (xcd - r) * q) + off; }
; __global__ void __launch_bounds__(NTHR, 2) fwd_megakernel(Args a) {
;     ...
;         pg8::Gemm g{H, WoT, M, DM, DM}; pg8::StaticOrderW<4> S; S.init(M, DM, G, blk);
;         pg8::EpiRes3 E{x, out, mod, g2, H2, part};
;         pg8::gemm_phase<pg8::EpiRes3, pg8::StaticOrderW<4>, true, true>(lds, g, S, E);
.LBB0_663:
	s_or_b64 exec, exec, s[2:3]
	v_readfirstlane_b32 s98, v237
	s_and_b32 s98, s98, 4
	s_cmp_eq_u32 s98, 0
	s_cbranch_scc1 .Lskew_skip
	s_sleep 127
	s_sleep 127
	s_sleep 127
	s_sleep 127
.Lskew_skip:
	v_readlane_b32 s4, v235, 7
	v_readlane_b32 s5, v235, 8
	s_mov_b64 s[2:3], -1
	s_and_b64 vcc, exec, s[4:5]
	s_waitcnt lgkmcnt(0)
	s_barrier
	s_cbranch_vccz .LBB0_874
	v_mov_b32_e32 v8, v186
	s_and_b64 vcc, exec, s[0:1]
	v_readfirstlane_b32 s5, v8
	s_cbranch_vccnz .LBB0_688
	s_ashr_i32 s33, s62, 31
	s_lshr_b32 s2, s33, 29
	s_add_i32 s6, s62, s2
	s_and_b32 s2, s6, -8
	s_sub_i32 s7, s62, s2
	s_cmp_gt_i32 s7, -1
	s_cbranch_scc0 .LBB0_667
	s_lshl_b32 s4, s7, 6
	s_cbranch_execz .LBB0_668
	s_branch .LBB0_669
